# next-unit queue atomic returns directly into its holding register and is waited for only where it is published (unit end)
# baseline (speedup 1.0000x reference)
; DI void phase_attn_fast(Frame& F, int l) {
;     ...
;     if (tid == 0) qidx[0] = (int)atomicAdd(ctr, 1u);
;     for (;;) {
;         __syncthreads();
;         const int i = qidx[0];
;         if (i >= 1024) break;
;         unsigned nxt = 0u; if (tid == 0) nxt = atomicAdd(ctr, 1u);
.LBB0_1333:
	v_readlane_b32 s10, v254, 14
	s_waitcnt lgkmcnt(0)
	s_barrier
	v_mov_b32_e32 v0, s10
	ds_read_b32 v0, v0
	s_movk_i32 s10, 0x3ff
	s_waitcnt lgkmcnt(0)
	v_cmp_lt_i32_e64 s[44:45], s10, v0
	v_readfirstlane_b32 s88, v0
	s_and_b64 vcc, exec, s[44:45]
	s_cbranch_vccnz .LBB0_1380
	v_mov_b32_e32 v200, 0
	s_and_saveexec_b64 s[10:11], s[74:75]
	s_cbranch_execz .LBB0_1338
	s_mov_b64 s[46:47], exec
	v_mbcnt_lo_u32_b32 v0, s46, 0
	v_mbcnt_hi_u32_b32 v0, s47, v0
	v_cmp_eq_u32_e32 vcc, 0, v0
	s_and_saveexec_b64 s[16:17], vcc
	s_cbranch_execz .LBB0_1337
	s_bcnt1_i32_b64 s22, s[46:47]
	v_mov_b32_e32 v2, s22
	v_readlane_b32 s22, v254, 63
	v_readlane_b32 s23, v255, 0
	s_nop 4
	global_atomic_add v200, v1, v2, s[22:23] sc0
.LBB0_1337:
	s_or_b64 exec, exec, s[16:17]
.LBB0_1338:
	s_or_b64 exec, exec, s[10:11]
	s_xor_b64 s[16:17], s[8:9], -1
	v_mov_b32_e32 v201, v184
	s_mov_b64 s[10:11], -1
	s_cmpk_gt_i32 s88, 0x1ff
	s_mov_b64 s[46:47], -1
	s_cbranch_scc0 .LBB0_1477
	s_andn2_b64 vcc, exec, s[16:17]
	s_mov_b32 s53, 0xefa18f08
	s_cbranch_vccnz .LBB0_1344
	s_and_saveexec_b64 s[16:17], s[74:75]
	s_cbranch_execz .LBB0_1343
	global_load_dword v0, v1, s[70:71] sc1
	s_waitcnt vmcnt(0)
	v_cmp_lt_u32_e32 vcc, 15, v0
	s_cbranch_vccnz .LBB0_1343

; DI void phase_attn_fast(Frame& F, int l) {
;     ...
;         __syncthreads();
;         if (tid == 0) qidx[0] = (int)nxt;
.LBB0_1507:
	s_nop 0
	v_cvt_pk_bf16_f32 v5, v2, v3
	global_store_dwordx2 v[34:35], v[4:5], off offset:112
	s_barrier
	s_and_saveexec_b64 s[8:9], s[74:75]
	s_cbranch_execz .LBB0_1332
	v_readlane_b32 s16, v254, 14
	s_nop 1
	v_mov_b32_e32 v0, s16
	s_waitcnt vmcnt(0)
	ds_write_b32 v0, v200
	s_branch .LBB0_1332
